# grid barrier: non-leader workgroups issue their agent-scope invalidate at arrival (before the arrival atomic) instead of after release; leader still invalidates L2 before releasing its XCD
# speedup vs baseline: 1.0114x; 1.0094x over previous
.Lgs0_b155:
	s_waitcnt vmcnt(0)
	s_barrier
	s_mov_b64 s[0:1], exec
	v_readlane_b32 s18, v254, 2
	v_readlane_b32 s19, v254, 3
	s_and_b64 s[18:19], s[0:1], s[18:19]
	s_mov_b64 exec, s[18:19]
	s_cbranch_execz .Lgs0_end
	buffer_inv sc1
	v_readlane_b32 s18, v255, 23
	s_waitcnt vmcnt(0) expcnt(0) lgkmcnt(0)
	s_nop 0
	v_mov_b32_e32 v0, s18
	ds_read_b32 v2, v0
	v_readlane_b32 s18, v255, 24
	s_waitcnt lgkmcnt(0)
	v_cmp_ne_u32_e32 vcc, 0, v2
	v_mov_b32_e32 v0, s18
	ds_read_b32 v0, v0
	s_cbranch_vccnz .Lgs0_b171
	s_mov_b32 s24, 1
	s_branch .Lgs0_b159

.Lgs0_b186:
	s_or_b64 exec, exec, s[22:23]
	s_waitcnt vmcnt(0)
	s_nop 0
	s_waitcnt vmcnt(0)

.Ldc_w1_skip:
.LBB0_227:
	s_waitcnt vmcnt(0)
	s_waitcnt vmcnt(0)
	s_barrier
	s_mov_b64 s[0:1], exec
	v_readlane_b32 s18, v254, 2
	v_readlane_b32 s19, v254, 3
	s_and_b64 s[18:19], s[0:1], s[18:19]
	s_mov_b64 exec, s[18:19]
	s_cbranch_execz .LBB0_279
	buffer_inv sc1
	v_readlane_b32 s18, v255, 23
	s_waitcnt vmcnt(0) expcnt(0) lgkmcnt(0)
	s_nop 0
	v_mov_b32_e32 v0, s18
	ds_read_b32 v2, v0
	v_readlane_b32 s18, v255, 24
	s_waitcnt lgkmcnt(0)
	v_cmp_ne_u32_e32 vcc, 0, v2
	v_mov_b32_e32 v0, s18
	ds_read_b32 v0, v0
	s_cbranch_vccnz .LBB0_243
	s_mov_b32 s24, 1
	s_branch .LBB0_231

.LBB0_656:
	s_waitcnt vmcnt(0)
	s_waitcnt vmcnt(0)
	s_barrier
	s_mov_b64 s[0:1], exec
	v_readlane_b32 s14, v254, 2
	v_readlane_b32 s15, v254, 3
	s_and_b64 s[14:15], s[0:1], s[14:15]
	s_mov_b64 exec, s[14:15]
	s_cbranch_execz .LBB0_708
	buffer_inv sc1
	v_readlane_b32 s14, v255, 23
	s_waitcnt vmcnt(0) expcnt(0) lgkmcnt(0)
	s_nop 0
	v_mov_b32_e32 v0, s14
	ds_read_b32 v2, v0
	v_readlane_b32 s14, v255, 24
	s_waitcnt lgkmcnt(0)
	v_cmp_ne_u32_e32 vcc, 0, v2
	v_mov_b32_e32 v0, s14
	ds_read_b32 v0, v0
	s_cbranch_vccnz .LBB0_672
	s_mov_b32 s26, 1
	s_branch .LBB0_660

.LBB0_687:
	s_or_b64 exec, exec, s[18:19]
	s_waitcnt vmcnt(0)
	s_nop 0
	s_waitcnt vmcnt(0)

.LBB0_724:
	s_waitcnt vmcnt(0)
	s_barrier
	s_mov_b64 s[0:1], exec
	v_readlane_b32 s14, v254, 2
	v_readlane_b32 s15, v254, 3
	s_and_b64 s[14:15], s[0:1], s[14:15]
	s_mov_b64 exec, s[14:15]
	s_cbranch_execz .LBB0_776
	buffer_inv sc1
	v_readlane_b32 s14, v255, 23
	s_waitcnt vmcnt(0) expcnt(0) lgkmcnt(0)
	s_nop 0
	v_mov_b32_e32 v0, s14
	ds_read_b32 v2, v0
	v_readlane_b32 s14, v255, 24
	s_waitcnt lgkmcnt(0)
	v_cmp_ne_u32_e32 vcc, 0, v2
	v_mov_b32_e32 v0, s14
	ds_read_b32 v0, v0
	s_cbranch_vccnz .LBB0_740
	s_mov_b32 s24, 1
	s_branch .LBB0_728

.Ldc_u0_skip:
.LBB0_804:
	s_waitcnt vmcnt(0)
	s_waitcnt vmcnt(0) lgkmcnt(0)
	s_barrier
	s_mov_b64 s[0:1], exec
	v_readlane_b32 s14, v254, 2
	v_readlane_b32 s15, v254, 3
	s_and_b64 s[14:15], s[0:1], s[14:15]
	s_mov_b64 exec, s[14:15]
	s_cbranch_execz .LBB0_856
	buffer_inv sc1
	v_readlane_b32 s14, v255, 23
	s_waitcnt vmcnt(0) expcnt(0) lgkmcnt(0)
	s_nop 0
	v_mov_b32_e32 v0, s14
	ds_read_b32 v2, v0
	v_readlane_b32 s14, v255, 24
	s_waitcnt lgkmcnt(0)
	v_cmp_ne_u32_e32 vcc, 0, v2
	v_mov_b32_e32 v0, s14
	ds_read_b32 v0, v0
	s_cbranch_vccnz .LBB0_820
	s_mov_b32 s26, 1
	s_branch .LBB0_808

.LBB0_859:
	s_or_b64 exec, exec, s[0:1]
	s_waitcnt vmcnt(0)
	s_barrier
	s_mov_b64 s[0:1], exec
	v_readlane_b32 s14, v254, 2
	v_readlane_b32 s15, v254, 3
	s_and_b64 s[14:15], s[0:1], s[14:15]
	s_mov_b64 exec, s[14:15]
	s_cbranch_execz .LBB0_911
	buffer_inv sc1
	v_readlane_b32 s14, v255, 23
	s_waitcnt vmcnt(0) expcnt(0) lgkmcnt(0)
	s_nop 0
	v_mov_b32_e32 v0, s14
	ds_read_b32 v2, v0
	v_readlane_b32 s14, v255, 24
	s_waitcnt lgkmcnt(0)
	v_cmp_ne_u32_e32 vcc, 0, v2
	v_mov_b32_e32 v0, s14
	ds_read_b32 v0, v0
	s_cbranch_vccnz .LBB0_875
	s_mov_b32 s26, 1
	s_branch .LBB0_863

.Ldc_w0_skip:
.LBB0_927:
	s_waitcnt vmcnt(0)
	s_waitcnt vmcnt(0)
	s_barrier
	s_mov_b64 s[0:1], exec
	v_readlane_b32 s14, v254, 2
	v_readlane_b32 s15, v254, 3
	v_readlane_b32 s62, v255, 37
	s_and_b64 s[14:15], s[0:1], s[14:15]
	v_readlane_b32 s63, v255, 38
	s_mov_b64 exec, s[14:15]
	s_cbranch_execz .LBB0_979
	buffer_inv sc1
	v_readlane_b32 s14, v255, 23
	s_waitcnt vmcnt(0) expcnt(0) lgkmcnt(0)
	s_nop 0
	v_mov_b32_e32 v0, s14
	ds_read_b32 v2, v0
	v_readlane_b32 s14, v255, 24
	s_waitcnt lgkmcnt(0)
	v_cmp_ne_u32_e32 vcc, 0, v2
	v_mov_b32_e32 v0, s14
	ds_read_b32 v0, v0
	s_cbranch_vccnz .LBB0_943
	s_mov_b32 s26, 1
	s_branch .LBB0_931

.LBB0_1002:
	buffer_inv sc1
	v_readlane_b32 s14, v255, 23
	s_waitcnt vmcnt(0) expcnt(0) lgkmcnt(0)
	s_nop 0
	v_mov_b32_e32 v0, s14
	ds_read_b32 v2, v0
	v_readlane_b32 s14, v255, 24
	s_waitcnt lgkmcnt(0)
	v_cmp_ne_u32_e32 vcc, 0, v2
	v_mov_b32_e32 v0, s14
	ds_read_b32 v0, v0
	s_cbranch_vccnz .LBB0_1017
	s_mov_b32 s24, 1
	s_branch .LBB0_1005
